# attention: wave priority inverted - raised during the softmax (VALU) segments, lowered during the MFMA blocks
# speedup vs baseline: 1.0024x; 1.0024x over previous
.Lat_noload_A:
	v_add_u32_e32 v193, s44, v164
	v_add_u32_e32 v194, s1, v168
	s_setprio 0
	ds_read_b128 v[204:207], v193
	ds_read_b128 v[208:211], v193 offset:6656
	ds_read_b128 v[212:215], v193 offset:13312
	ds_read_b128 v[216:219], v193 offset:19968
	ds_read_b128 v[220:223], v193 offset:64
	ds_read_b128 v[224:227], v193 offset:6720
	ds_read_b128 v[228:231], v193 offset:13376
	ds_read_b128 v[232:235], v193 offset:20032
	s_waitcnt lgkmcnt(7)
	v_mfma_f32_16x16x32_bf16 v[132:135], v[204:207], v[64:67], 0
	v_mfma_f32_16x16x32_bf16 v[136:139], v[204:207], v[88:91], 0
	ds_read_b128 v[204:207], v193 offset:128
	s_waitcnt lgkmcnt(7)
	v_mfma_f32_16x16x32_bf16 v[140:143], v[208:211], v[64:67], 0
	v_mfma_f32_16x16x32_bf16 v[144:147], v[208:211], v[88:91], 0
	ds_read_b128 v[208:211], v193 offset:6784
	s_waitcnt lgkmcnt(7)
	v_mfma_f32_16x16x32_bf16 v[148:151], v[212:215], v[64:67], 0
	v_mfma_f32_16x16x32_bf16 v[152:155], v[212:215], v[88:91], 0
	ds_read_b128 v[212:215], v193 offset:13440
	s_waitcnt lgkmcnt(7)
	v_mfma_f32_16x16x32_bf16 v[156:159], v[216:219], v[64:67], 0
	v_mfma_f32_16x16x32_bf16 v[160:163], v[216:219], v[88:91], 0
	ds_read_b128 v[216:219], v193 offset:20096
	s_waitcnt lgkmcnt(7)
	v_mfma_f32_16x16x32_bf16 v[132:135], v[220:223], v[68:71], v[132:135]
	v_mfma_f32_16x16x32_bf16 v[136:139], v[220:223], v[92:95], v[136:139]
	ds_read_b128 v[220:223], v193 offset:192
	s_waitcnt lgkmcnt(7)
	v_mfma_f32_16x16x32_bf16 v[140:143], v[224:227], v[68:71], v[140:143]
	v_mfma_f32_16x16x32_bf16 v[144:147], v[224:227], v[92:95], v[144:147]
	ds_read_b128 v[224:227], v193 offset:6848
	s_waitcnt lgkmcnt(7)
	v_mfma_f32_16x16x32_bf16 v[148:151], v[228:231], v[68:71], v[148:151]
	v_mfma_f32_16x16x32_bf16 v[152:155], v[228:231], v[92:95], v[152:155]
	ds_read_b128 v[228:231], v193 offset:13504
	s_waitcnt lgkmcnt(7)
	v_mfma_f32_16x16x32_bf16 v[156:159], v[232:235], v[68:71], v[156:159]
	v_mfma_f32_16x16x32_bf16 v[160:163], v[232:235], v[92:95], v[160:163]
	ds_read_b128 v[232:235], v193 offset:20160
	s_waitcnt lgkmcnt(7)
	v_mfma_f32_16x16x32_bf16 v[132:135], v[204:207], v[72:75], v[132:135]
	v_mfma_f32_16x16x32_bf16 v[136:139], v[204:207], v[96:99], v[136:139]
	ds_read_b128 v[204:207], v193 offset:256
	s_waitcnt lgkmcnt(7)
	v_mfma_f32_16x16x32_bf16 v[140:143], v[208:211], v[72:75], v[140:143]
	v_mfma_f32_16x16x32_bf16 v[144:147], v[208:211], v[96:99], v[144:147]
	ds_read_b128 v[208:211], v193 offset:6912
	s_waitcnt lgkmcnt(7)
	v_mfma_f32_16x16x32_bf16 v[148:151], v[212:215], v[72:75], v[148:151]
	v_mfma_f32_16x16x32_bf16 v[152:155], v[212:215], v[96:99], v[152:155]
	ds_read_b128 v[212:215], v193 offset:13568
	s_waitcnt lgkmcnt(7)
	v_mfma_f32_16x16x32_bf16 v[156:159], v[216:219], v[72:75], v[156:159]
	v_mfma_f32_16x16x32_bf16 v[160:163], v[216:219], v[96:99], v[160:163]
	ds_read_b128 v[216:219], v193 offset:20224
	s_waitcnt lgkmcnt(7)
	v_mfma_f32_16x16x32_bf16 v[132:135], v[220:223], v[76:79], v[132:135]
	v_mfma_f32_16x16x32_bf16 v[136:139], v[220:223], v[100:103], v[136:139]
	ds_read_b128 v[220:223], v193 offset:320
	s_waitcnt lgkmcnt(7)
	v_mfma_f32_16x16x32_bf16 v[140:143], v[224:227], v[76:79], v[140:143]
	v_mfma_f32_16x16x32_bf16 v[144:147], v[224:227], v[100:103], v[144:147]
	ds_read_b128 v[224:227], v193 offset:6976
	s_waitcnt lgkmcnt(7)
	v_mfma_f32_16x16x32_bf16 v[148:151], v[228:231], v[76:79], v[148:151]
	v_mfma_f32_16x16x32_bf16 v[152:155], v[228:231], v[100:103], v[152:155]
	ds_read_b128 v[228:231], v193 offset:13632
	s_waitcnt lgkmcnt(7)
	v_mfma_f32_16x16x32_bf16 v[156:159], v[232:235], v[76:79], v[156:159]
	v_mfma_f32_16x16x32_bf16 v[160:163], v[232:235], v[100:103], v[160:163]
	ds_read_b128 v[232:235], v193 offset:20288
	s_waitcnt lgkmcnt(7)
	v_mfma_f32_16x16x32_bf16 v[132:135], v[204:207], v[80:83], v[132:135]
	v_mfma_f32_16x16x32_bf16 v[136:139], v[204:207], v[104:107], v[136:139]
	ds_read_b128 v[204:207], v194
	s_waitcnt lgkmcnt(7)
	v_mfma_f32_16x16x32_bf16 v[140:143], v[208:211], v[80:83], v[140:143]
	v_mfma_f32_16x16x32_bf16 v[144:147], v[208:211], v[104:107], v[144:147]
	ds_read_b128 v[208:211], v194 offset:64
	s_waitcnt lgkmcnt(7)
	v_mfma_f32_16x16x32_bf16 v[148:151], v[212:215], v[80:83], v[148:151]
	v_mfma_f32_16x16x32_bf16 v[152:155], v[212:215], v[104:107], v[152:155]
	ds_read_b128 v[212:215], v194 offset:2560
	s_waitcnt lgkmcnt(7)
	v_mfma_f32_16x16x32_bf16 v[156:159], v[216:219], v[80:83], v[156:159]
	v_mfma_f32_16x16x32_bf16 v[160:163], v[216:219], v[104:107], v[160:163]
	ds_read_b128 v[216:219], v194 offset:2624
	s_waitcnt lgkmcnt(7)
	v_mfma_f32_16x16x32_bf16 v[132:135], v[220:223], v[84:87], v[132:135]
	v_mfma_f32_16x16x32_bf16 v[136:139], v[220:223], v[108:111], v[136:139]
	ds_read_b128 v[220:223], v194 offset:5120
	s_waitcnt lgkmcnt(7)
	v_mfma_f32_16x16x32_bf16 v[140:143], v[224:227], v[84:87], v[140:143]
	v_mfma_f32_16x16x32_bf16 v[144:147], v[224:227], v[108:111], v[144:147]
	ds_read_b128 v[224:227], v194 offset:5184
	s_waitcnt lgkmcnt(7)
	v_mfma_f32_16x16x32_bf16 v[148:151], v[228:231], v[84:87], v[148:151]
	v_mfma_f32_16x16x32_bf16 v[152:155], v[228:231], v[108:111], v[152:155]
	ds_read_b128 v[228:231], v194 offset:7680
	s_waitcnt lgkmcnt(7)
	v_mfma_f32_16x16x32_bf16 v[156:159], v[232:235], v[84:87], v[156:159]
	v_mfma_f32_16x16x32_bf16 v[160:163], v[232:235], v[108:111], v[160:163]
	ds_read_b128 v[232:235], v194 offset:7744
	s_setprio 1
	s_nop 6
	v_max3_f32 v199, v132, v133, v134
	v_max3_f32 v200, v136, v137, v138
	v_max3_f32 v199, v199, v135, v140
	v_max3_f32 v200, v200, v139, v144
	v_max3_f32 v199, v199, v141, v142
	v_max3_f32 v200, v200, v145, v146
	v_max3_f32 v199, v199, v143, v148
	v_max3_f32 v200, v200, v147, v152
	v_max3_f32 v199, v199, v149, v150
	v_max3_f32 v200, v200, v153, v154
	v_max3_f32 v199, v199, v151, v156
	v_max3_f32 v200, v200, v155, v160
	v_max3_f32 v199, v199, v157, v158
	v_max3_f32 v200, v200, v161, v162
	v_max_f32_e32 v199, v199, v159
	v_max_f32_e32 v200, v200, v163
	v_mov_b32_e32 v253, v199
	v_mov_b32_e32 v201, v200
	s_nop 1
	v_permlane16_swap_b32_e32 v199, v253
	v_permlane16_swap_b32_e32 v200, v201
	s_nop 0
	v_max_f32_e32 v199, v199, v253
	v_max_f32_e32 v200, v200, v201
	v_mov_b32_e32 v253, v199
	v_mov_b32_e32 v201, v200
	s_nop 1
	v_permlane32_swap_b32_e32 v199, v253
	v_permlane32_swap_b32_e32 v200, v201
	s_nop 0
	v_max_f32_e32 v199, v199, v253
	v_max_f32_e32 v200, v200, v201
	v_max_f32_e32 v199, v177, v199
	v_max_f32_e32 v200, v178, v200
	v_sub_f32_e32 v182, v177, v199
	v_sub_f32_e32 v202, v178, v200
	v_exp_f32_e32 v182, v182
	v_exp_f32_e32 v202, v202
	v_mov_b32_e32 v177, v199
	v_mov_b32_e32 v178, v200
	v_sub_f32_e32 v132, v132, v177
	v_sub_f32_e32 v136, v136, v178
	v_sub_f32_e32 v133, v133, v177
	v_sub_f32_e32 v137, v137, v178
	v_sub_f32_e32 v134, v134, v177
	v_sub_f32_e32 v138, v138, v178
	v_sub_f32_e32 v135, v135, v177
	v_sub_f32_e32 v139, v139, v178
	v_sub_f32_e32 v140, v140, v177
	v_sub_f32_e32 v144, v144, v178
	v_sub_f32_e32 v141, v141, v177
	v_sub_f32_e32 v145, v145, v178
	v_sub_f32_e32 v142, v142, v177
	v_sub_f32_e32 v146, v146, v178
	v_sub_f32_e32 v143, v143, v177
	v_sub_f32_e32 v147, v147, v178
	v_sub_f32_e32 v148, v148, v177
	v_sub_f32_e32 v152, v152, v178
	v_sub_f32_e32 v149, v149, v177
	v_sub_f32_e32 v153, v153, v178
	v_sub_f32_e32 v150, v150, v177
	v_sub_f32_e32 v154, v154, v178
	v_sub_f32_e32 v151, v151, v177
	v_sub_f32_e32 v155, v155, v178
	v_sub_f32_e32 v156, v156, v177
	v_sub_f32_e32 v160, v160, v178
	v_sub_f32_e32 v157, v157, v177
	v_sub_f32_e32 v161, v161, v178
	v_sub_f32_e32 v158, v158, v177
	v_sub_f32_e32 v162, v162, v178
	v_sub_f32_e32 v159, v159, v177
	v_sub_f32_e32 v163, v163, v178
	v_exp_f32_e32 v132, v132
	v_exp_f32_e32 v136, v136
	v_exp_f32_e32 v133, v133
	v_exp_f32_e32 v137, v137
	v_exp_f32_e32 v134, v134
	v_exp_f32_e32 v138, v138
	v_exp_f32_e32 v135, v135
	v_exp_f32_e32 v139, v139
	v_exp_f32_e32 v140, v140
	v_exp_f32_e32 v144, v144
	v_exp_f32_e32 v141, v141
	v_exp_f32_e32 v145, v145
	v_exp_f32_e32 v142, v142
	v_exp_f32_e32 v146, v146
	v_exp_f32_e32 v143, v143
	v_exp_f32_e32 v147, v147
	v_exp_f32_e32 v148, v148
	v_exp_f32_e32 v152, v152
	v_exp_f32_e32 v149, v149
	v_exp_f32_e32 v153, v153
	v_exp_f32_e32 v150, v150
	v_exp_f32_e32 v154, v154
	v_exp_f32_e32 v151, v151
	v_exp_f32_e32 v155, v155
	v_exp_f32_e32 v156, v156
	v_exp_f32_e32 v160, v160
	v_exp_f32_e32 v157, v157
	v_exp_f32_e32 v161, v161
	v_exp_f32_e32 v158, v158
	v_exp_f32_e32 v162, v162
	v_exp_f32_e32 v159, v159
	v_exp_f32_e32 v163, v163
	v_cmp_eq_f32_e32 vcc, 1.0, v182
	s_cmp_eq_u64 vcc, exec
	s_cbranch_scc1 .Lat_noscale0_A
	v_pk_mul_f32 v[0:1], v[0:1], v[182:183] op_sel_hi:[1,0]
	v_pk_mul_f32 v[2:3], v[2:3], v[182:183] op_sel_hi:[1,0]
	v_pk_mul_f32 v[8:9], v[8:9], v[182:183] op_sel_hi:[1,0]
	v_pk_mul_f32 v[10:11], v[10:11], v[182:183] op_sel_hi:[1,0]
	v_pk_mul_f32 v[16:17], v[16:17], v[182:183] op_sel_hi:[1,0]
	v_pk_mul_f32 v[18:19], v[18:19], v[182:183] op_sel_hi:[1,0]
	v_pk_mul_f32 v[24:25], v[24:25], v[182:183] op_sel_hi:[1,0]
	v_pk_mul_f32 v[26:27], v[26:27], v[182:183] op_sel_hi:[1,0]
	v_pk_mul_f32 v[32:33], v[32:33], v[182:183] op_sel_hi:[1,0]
	v_pk_mul_f32 v[34:35], v[34:35], v[182:183] op_sel_hi:[1,0]
	v_pk_mul_f32 v[40:41], v[40:41], v[182:183] op_sel_hi:[1,0]
	v_pk_mul_f32 v[42:43], v[42:43], v[182:183] op_sel_hi:[1,0]
	v_pk_mul_f32 v[48:49], v[48:49], v[182:183] op_sel_hi:[1,0]
	v_pk_mul_f32 v[50:51], v[50:51], v[182:183] op_sel_hi:[1,0]
	v_pk_mul_f32 v[56:57], v[56:57], v[182:183] op_sel_hi:[1,0]
	v_pk_mul_f32 v[58:59], v[58:59], v[182:183] op_sel_hi:[1,0]

.Lat_noscale1_A:
	v_add_f32_e32 v183, v132, v133
	v_add_f32_e32 v203, v136, v137
	v_add_f32_e32 v183, v183, v134
	v_add_f32_e32 v203, v203, v138
	v_add_f32_e32 v183, v183, v135
	v_add_f32_e32 v203, v203, v139
	v_add_f32_e32 v183, v183, v140
	v_add_f32_e32 v203, v203, v144
	v_add_f32_e32 v183, v183, v141
	v_add_f32_e32 v203, v203, v145
	v_add_f32_e32 v183, v183, v142
	v_add_f32_e32 v203, v203, v146
	v_add_f32_e32 v183, v183, v143
	v_add_f32_e32 v203, v203, v147
	v_add_f32_e32 v183, v183, v148
	v_add_f32_e32 v203, v203, v152
	v_add_f32_e32 v183, v183, v149
	v_add_f32_e32 v203, v203, v153
	v_add_f32_e32 v183, v183, v150
	v_add_f32_e32 v203, v203, v154
	v_add_f32_e32 v183, v183, v151
	v_add_f32_e32 v203, v203, v155
	v_add_f32_e32 v183, v183, v156
	v_add_f32_e32 v203, v203, v160
	v_add_f32_e32 v183, v183, v157
	v_add_f32_e32 v203, v203, v161
	v_add_f32_e32 v183, v183, v158
	v_add_f32_e32 v203, v203, v162
	v_add_f32_e32 v183, v183, v159
	v_add_f32_e32 v203, v203, v163
	v_fmac_f32_e32 v183, v179, v182
	v_fmac_f32_e32 v203, v180, v202
	v_mov_b32_e32 v179, v183
	v_mov_b32_e32 v180, v203
	v_cvt_pk_bf16_f32 v236, v132, v133
	v_cvt_pk_bf16_f32 v237, v134, v135
	v_cvt_pk_bf16_f32 v238, v140, v141
	v_cvt_pk_bf16_f32 v239, v142, v143
	v_cvt_pk_bf16_f32 v244, v136, v137
	v_cvt_pk_bf16_f32 v245, v138, v139
	v_cvt_pk_bf16_f32 v246, v144, v145
	v_cvt_pk_bf16_f32 v247, v146, v147
	v_cvt_pk_bf16_f32 v240, v148, v149
	v_cvt_pk_bf16_f32 v241, v150, v151
	v_cvt_pk_bf16_f32 v242, v156, v157
	v_cvt_pk_bf16_f32 v243, v158, v159
	v_cvt_pk_bf16_f32 v248, v152, v153
	v_cvt_pk_bf16_f32 v249, v154, v155
	v_cvt_pk_bf16_f32 v250, v160, v161
	v_cvt_pk_bf16_f32 v251, v162, v163
	s_setprio 0
	s_nop 0
	s_waitcnt lgkmcnt(7)
	v_mfma_f32_16x16x32_bf16 v[0:3], v[204:207], v[236:239], v[0:3]
	v_mfma_f32_16x16x32_bf16 v[4:7], v[204:207], v[244:247], v[4:7]
	ds_read_b128 v[204:207], v194 offset:10240
	s_waitcnt lgkmcnt(7)
	v_mfma_f32_16x16x32_bf16 v[0:3], v[208:211], v[240:243], v[0:3]
	v_mfma_f32_16x16x32_bf16 v[4:7], v[208:211], v[248:251], v[4:7]
	ds_read_b128 v[208:211], v194 offset:10304
	s_waitcnt lgkmcnt(7)
	v_mfma_f32_16x16x32_bf16 v[8:11], v[212:215], v[236:239], v[8:11]
	v_mfma_f32_16x16x32_bf16 v[12:15], v[212:215], v[244:247], v[12:15]
	ds_read_b128 v[212:215], v194 offset:12800
	s_waitcnt lgkmcnt(7)
	v_mfma_f32_16x16x32_bf16 v[8:11], v[216:219], v[240:243], v[8:11]
	v_mfma_f32_16x16x32_bf16 v[12:15], v[216:219], v[248:251], v[12:15]
	ds_read_b128 v[216:219], v194 offset:12864
	s_waitcnt lgkmcnt(7)
	v_mfma_f32_16x16x32_bf16 v[16:19], v[220:223], v[236:239], v[16:19]
	v_mfma_f32_16x16x32_bf16 v[20:23], v[220:223], v[244:247], v[20:23]
	ds_read_b128 v[220:223], v194 offset:15360
	s_waitcnt lgkmcnt(7)
	v_mfma_f32_16x16x32_bf16 v[16:19], v[224:227], v[240:243], v[16:19]
	v_mfma_f32_16x16x32_bf16 v[20:23], v[224:227], v[248:251], v[20:23]
	ds_read_b128 v[224:227], v194 offset:15424
	s_waitcnt lgkmcnt(7)
	v_mfma_f32_16x16x32_bf16 v[24:27], v[228:231], v[236:239], v[24:27]
	v_mfma_f32_16x16x32_bf16 v[28:31], v[228:231], v[244:247], v[28:31]
	ds_read_b128 v[228:231], v194 offset:17920
	s_waitcnt lgkmcnt(7)
	v_mfma_f32_16x16x32_bf16 v[24:27], v[232:235], v[240:243], v[24:27]
	v_mfma_f32_16x16x32_bf16 v[28:31], v[232:235], v[248:251], v[28:31]
	ds_read_b128 v[232:235], v194 offset:17984
	s_waitcnt lgkmcnt(7)
	v_mfma_f32_16x16x32_bf16 v[32:35], v[204:207], v[236:239], v[32:35]
	v_mfma_f32_16x16x32_bf16 v[36:39], v[204:207], v[244:247], v[36:39]
	s_waitcnt lgkmcnt(6)
	v_mfma_f32_16x16x32_bf16 v[32:35], v[208:211], v[240:243], v[32:35]
	v_mfma_f32_16x16x32_bf16 v[36:39], v[208:211], v[248:251], v[36:39]
	s_waitcnt lgkmcnt(5)
	v_mfma_f32_16x16x32_bf16 v[40:43], v[212:215], v[236:239], v[40:43]
	v_mfma_f32_16x16x32_bf16 v[44:47], v[212:215], v[244:247], v[44:47]
	s_waitcnt lgkmcnt(4)
	v_mfma_f32_16x16x32_bf16 v[40:43], v[216:219], v[240:243], v[40:43]
	v_mfma_f32_16x16x32_bf16 v[44:47], v[216:219], v[248:251], v[44:47]
	s_waitcnt lgkmcnt(3)
	v_mfma_f32_16x16x32_bf16 v[48:51], v[220:223], v[236:239], v[48:51]
	v_mfma_f32_16x16x32_bf16 v[52:55], v[220:223], v[244:247], v[52:55]
	s_waitcnt lgkmcnt(2)
	v_mfma_f32_16x16x32_bf16 v[48:51], v[224:227], v[240:243], v[48:51]
	v_mfma_f32_16x16x32_bf16 v[52:55], v[224:227], v[248:251], v[52:55]
	s_waitcnt lgkmcnt(1)
	v_mfma_f32_16x16x32_bf16 v[56:59], v[228:231], v[236:239], v[56:59]
	v_mfma_f32_16x16x32_bf16 v[60:63], v[228:231], v[244:247], v[60:63]
	s_waitcnt lgkmcnt(0)
	v_mfma_f32_16x16x32_bf16 v[56:59], v[232:235], v[240:243], v[56:59]
	v_mfma_f32_16x16x32_bf16 v[60:63], v[232:235], v[248:251], v[60:63]
	s_setprio 1
	s_cmpk_lt_u32 s35, 67
	s_cbranch_scc0 .Lat_nostage_A
	s_xor_b32 s12, s44, 26624
	v_add_u32_e32 v195, s12, v169
	v_add_u32_e32 v196, s12, v170
	v_add_u32_e32 v197, s13, v171
	v_add_u32_e32 v198, 10240, v197
	s_waitcnt vmcnt(0)
	ds_write_b128 v195, v[112:115]
	ds_write_b128 v195, v[116:119] offset:13312
	ds_write_b128 v196, v[120:123]
	ds_write2_b64 v197, v[124:125], v[126:127] offset1:2
	ds_write2_b64 v198, v[128:129], v[130:131] offset1:2

.Lat_noload_B0:
	v_add_u32_e32 v193, s44, v164
	v_add_u32_e32 v252, s1, v168
	s_setprio 0
	ds_read_b128 v[204:207], v193
	ds_read_b128 v[208:211], v193 offset:6656
	ds_read_b128 v[212:215], v193 offset:13312
	ds_read_b128 v[216:219], v193 offset:19968
	ds_read_b128 v[220:223], v193 offset:64
	ds_read_b128 v[224:227], v193 offset:6720
	ds_read_b128 v[228:231], v193 offset:13376
	ds_read_b128 v[232:235], v193 offset:20032
	s_waitcnt lgkmcnt(7)
	v_mfma_f32_16x16x32_bf16 v[132:135], v[204:207], v[64:67], 0
	v_mfma_f32_16x16x32_bf16 v[136:139], v[204:207], v[88:91], 0
	ds_read_b128 v[204:207], v193 offset:128
	s_waitcnt lgkmcnt(7)
	v_mfma_f32_16x16x32_bf16 v[140:143], v[208:211], v[64:67], 0
	v_mfma_f32_16x16x32_bf16 v[144:147], v[208:211], v[88:91], 0
	ds_read_b128 v[208:211], v193 offset:6784
	s_waitcnt lgkmcnt(7)
	v_mfma_f32_16x16x32_bf16 v[148:151], v[212:215], v[64:67], 0
	v_mfma_f32_16x16x32_bf16 v[152:155], v[212:215], v[88:91], 0
	ds_read_b128 v[212:215], v193 offset:13440
	s_waitcnt lgkmcnt(7)
	v_mfma_f32_16x16x32_bf16 v[156:159], v[216:219], v[64:67], 0
	v_mfma_f32_16x16x32_bf16 v[160:163], v[216:219], v[88:91], 0
	ds_read_b128 v[216:219], v193 offset:20096
	s_waitcnt lgkmcnt(7)
	v_mfma_f32_16x16x32_bf16 v[132:135], v[220:223], v[68:71], v[132:135]
	v_mfma_f32_16x16x32_bf16 v[136:139], v[220:223], v[92:95], v[136:139]
	ds_read_b128 v[220:223], v193 offset:192
	s_waitcnt lgkmcnt(7)
	v_mfma_f32_16x16x32_bf16 v[140:143], v[224:227], v[68:71], v[140:143]
	v_mfma_f32_16x16x32_bf16 v[144:147], v[224:227], v[92:95], v[144:147]
	ds_read_b128 v[224:227], v193 offset:6848
	s_waitcnt lgkmcnt(7)
	v_mfma_f32_16x16x32_bf16 v[148:151], v[228:231], v[68:71], v[148:151]
	v_mfma_f32_16x16x32_bf16 v[152:155], v[228:231], v[92:95], v[152:155]
	ds_read_b128 v[228:231], v193 offset:13504
	s_waitcnt lgkmcnt(7)
	v_mfma_f32_16x16x32_bf16 v[156:159], v[232:235], v[68:71], v[156:159]
	v_mfma_f32_16x16x32_bf16 v[160:163], v[232:235], v[92:95], v[160:163]
	ds_read_b128 v[232:235], v193 offset:20160
	s_waitcnt lgkmcnt(7)
	v_mfma_f32_16x16x32_bf16 v[132:135], v[204:207], v[72:75], v[132:135]
	v_mfma_f32_16x16x32_bf16 v[136:139], v[204:207], v[96:99], v[136:139]
	ds_read_b128 v[204:207], v193 offset:256
	s_waitcnt lgkmcnt(7)
	v_mfma_f32_16x16x32_bf16 v[140:143], v[208:211], v[72:75], v[140:143]
	v_mfma_f32_16x16x32_bf16 v[144:147], v[208:211], v[96:99], v[144:147]
	ds_read_b128 v[208:211], v193 offset:6912
	s_waitcnt lgkmcnt(7)
	v_mfma_f32_16x16x32_bf16 v[148:151], v[212:215], v[72:75], v[148:151]
	v_mfma_f32_16x16x32_bf16 v[152:155], v[212:215], v[96:99], v[152:155]
	ds_read_b128 v[212:215], v193 offset:13568
	s_waitcnt lgkmcnt(7)
	v_mfma_f32_16x16x32_bf16 v[156:159], v[216:219], v[72:75], v[156:159]
	v_mfma_f32_16x16x32_bf16 v[160:163], v[216:219], v[96:99], v[160:163]
	ds_read_b128 v[216:219], v193 offset:20224
	s_waitcnt lgkmcnt(7)
	v_mfma_f32_16x16x32_bf16 v[132:135], v[220:223], v[76:79], v[132:135]
	v_mfma_f32_16x16x32_bf16 v[136:139], v[220:223], v[100:103], v[136:139]
	ds_read_b128 v[220:223], v193 offset:320
	s_waitcnt lgkmcnt(7)
	v_mfma_f32_16x16x32_bf16 v[140:143], v[224:227], v[76:79], v[140:143]
	v_mfma_f32_16x16x32_bf16 v[144:147], v[224:227], v[100:103], v[144:147]
	ds_read_b128 v[224:227], v193 offset:6976
	s_waitcnt lgkmcnt(7)
	v_mfma_f32_16x16x32_bf16 v[148:151], v[228:231], v[76:79], v[148:151]
	v_mfma_f32_16x16x32_bf16 v[152:155], v[228:231], v[100:103], v[152:155]
	ds_read_b128 v[228:231], v193 offset:13632
	s_waitcnt lgkmcnt(7)
	v_mfma_f32_16x16x32_bf16 v[156:159], v[232:235], v[76:79], v[156:159]
	v_mfma_f32_16x16x32_bf16 v[160:163], v[232:235], v[100:103], v[160:163]
	ds_read_b128 v[232:235], v193 offset:20288
	s_waitcnt lgkmcnt(7)
	v_mfma_f32_16x16x32_bf16 v[132:135], v[204:207], v[80:83], v[132:135]
	v_mfma_f32_16x16x32_bf16 v[136:139], v[204:207], v[104:107], v[136:139]
	ds_read_b128 v[204:207], v252
	s_waitcnt lgkmcnt(7)
	v_mfma_f32_16x16x32_bf16 v[140:143], v[208:211], v[80:83], v[140:143]
	v_mfma_f32_16x16x32_bf16 v[144:147], v[208:211], v[104:107], v[144:147]
	ds_read_b128 v[208:211], v252 offset:64
	s_waitcnt lgkmcnt(7)
	v_mfma_f32_16x16x32_bf16 v[148:151], v[212:215], v[80:83], v[148:151]
	v_mfma_f32_16x16x32_bf16 v[152:155], v[212:215], v[104:107], v[152:155]
	ds_read_b128 v[212:215], v252 offset:2560
	s_waitcnt lgkmcnt(7)
	v_mfma_f32_16x16x32_bf16 v[156:159], v[216:219], v[80:83], v[156:159]
	v_mfma_f32_16x16x32_bf16 v[160:163], v[216:219], v[104:107], v[160:163]
	ds_read_b128 v[216:219], v252 offset:2624
	s_waitcnt lgkmcnt(7)
	v_mfma_f32_16x16x32_bf16 v[132:135], v[220:223], v[84:87], v[132:135]
	v_mfma_f32_16x16x32_bf16 v[136:139], v[220:223], v[108:111], v[136:139]
	ds_read_b128 v[220:223], v252 offset:5120
	s_waitcnt lgkmcnt(7)
	v_mfma_f32_16x16x32_bf16 v[140:143], v[224:227], v[84:87], v[140:143]
	v_mfma_f32_16x16x32_bf16 v[144:147], v[224:227], v[108:111], v[144:147]
	ds_read_b128 v[224:227], v252 offset:5184
	s_waitcnt lgkmcnt(7)
	v_mfma_f32_16x16x32_bf16 v[148:151], v[228:231], v[84:87], v[148:151]
	v_mfma_f32_16x16x32_bf16 v[152:155], v[228:231], v[108:111], v[152:155]
	ds_read_b128 v[228:231], v252 offset:7680
	s_waitcnt lgkmcnt(7)
	v_mfma_f32_16x16x32_bf16 v[156:159], v[232:235], v[84:87], v[156:159]
	v_mfma_f32_16x16x32_bf16 v[160:163], v[232:235], v[108:111], v[160:163]
	ds_read_b128 v[232:235], v252 offset:7744
	s_setprio 1
	s_nop 6
	v_max3_f32 v199, v132, v133, v134
	v_max3_f32 v200, v136, v137, v138
	v_max3_f32 v199, v199, v135, v140
	v_max3_f32 v200, v200, v139, v144
	v_max3_f32 v199, v199, v141, v142
	v_max3_f32 v200, v200, v145, v146
	v_max3_f32 v199, v199, v143, v148
	v_max3_f32 v200, v200, v147, v152
	v_max3_f32 v199, v199, v149, v150
	v_max3_f32 v200, v200, v153, v154
	v_max3_f32 v199, v199, v151, v156
	v_max3_f32 v200, v200, v155, v160
	v_max3_f32 v199, v199, v157, v158
	v_max3_f32 v200, v200, v161, v162
	v_max_f32_e32 v199, v199, v159
	v_max_f32_e32 v200, v200, v163
	v_mov_b32_e32 v253, v199
	v_mov_b32_e32 v201, v200
	s_nop 1
	v_permlane16_swap_b32_e32 v199, v253
	v_permlane16_swap_b32_e32 v200, v201
	s_nop 0
	v_max_f32_e32 v199, v199, v253
	v_max_f32_e32 v200, v200, v201
	v_mov_b32_e32 v253, v199
	v_mov_b32_e32 v201, v200
	s_nop 1
	v_permlane32_swap_b32_e32 v199, v253
	v_permlane32_swap_b32_e32 v200, v201
	s_nop 0
	v_max_f32_e32 v199, v199, v253
	v_max_f32_e32 v200, v200, v201
	v_max_f32_e32 v199, v177, v199
	v_max_f32_e32 v200, v178, v200
	v_sub_f32_e32 v182, v177, v199
	v_sub_f32_e32 v202, v178, v200
	v_exp_f32_e32 v182, v182
	v_exp_f32_e32 v202, v202
	v_mov_b32_e32 v177, v199
	v_mov_b32_e32 v178, v200
	v_sub_f32_e32 v132, v132, v177
	v_sub_f32_e32 v136, v136, v178
	v_sub_f32_e32 v133, v133, v177
	v_sub_f32_e32 v137, v137, v178
	v_sub_f32_e32 v134, v134, v177
	v_sub_f32_e32 v138, v138, v178
	v_sub_f32_e32 v135, v135, v177
	v_sub_f32_e32 v139, v139, v178
	v_sub_f32_e32 v140, v140, v177
	v_sub_f32_e32 v144, v144, v178
	v_sub_f32_e32 v141, v141, v177
	v_sub_f32_e32 v145, v145, v178
	v_sub_f32_e32 v142, v142, v177
	v_sub_f32_e32 v146, v146, v178
	v_sub_f32_e32 v143, v143, v177
	v_sub_f32_e32 v147, v147, v178
	v_sub_f32_e32 v148, v148, v177
	v_sub_f32_e32 v152, v152, v178
	v_sub_f32_e32 v149, v149, v177
	v_sub_f32_e32 v153, v153, v178
	v_sub_f32_e32 v150, v150, v177
	v_sub_f32_e32 v154, v154, v178
	v_sub_f32_e32 v151, v151, v177
	v_sub_f32_e32 v155, v155, v178
	v_sub_f32_e32 v156, v156, v177
	v_sub_f32_e32 v160, v160, v178
	v_sub_f32_e32 v157, v157, v177
	v_sub_f32_e32 v161, v161, v178
	v_sub_f32_e32 v158, v158, v177
	v_sub_f32_e32 v162, v162, v178
	v_sub_f32_e32 v159, v159, v177
	v_sub_f32_e32 v163, v163, v178
	v_exp_f32_e32 v132, v132
	v_exp_f32_e32 v136, v136
	v_exp_f32_e32 v133, v133
	v_exp_f32_e32 v137, v137
	v_exp_f32_e32 v134, v134
	v_exp_f32_e32 v138, v138
	v_exp_f32_e32 v135, v135
	v_exp_f32_e32 v139, v139
	v_exp_f32_e32 v140, v140
	v_exp_f32_e32 v144, v144
	v_exp_f32_e32 v141, v141
	v_exp_f32_e32 v145, v145
	v_exp_f32_e32 v142, v142
	v_exp_f32_e32 v146, v146
	v_exp_f32_e32 v143, v143
	v_exp_f32_e32 v147, v147
	v_exp_f32_e32 v148, v148
	v_exp_f32_e32 v152, v152
	v_exp_f32_e32 v149, v149
	v_exp_f32_e32 v153, v153
	v_exp_f32_e32 v150, v150
	v_exp_f32_e32 v154, v154
	v_exp_f32_e32 v151, v151
	v_exp_f32_e32 v155, v155
	v_exp_f32_e32 v156, v156
	v_exp_f32_e32 v160, v160
	v_exp_f32_e32 v157, v157
	v_exp_f32_e32 v161, v161
	v_exp_f32_e32 v158, v158
	v_exp_f32_e32 v162, v162
	v_exp_f32_e32 v159, v159
	v_exp_f32_e32 v163, v163
	v_cmp_eq_f32_e32 vcc, 1.0, v182
	s_cmp_eq_u64 vcc, exec
	s_cbranch_scc1 .Lat_noscale0_B0
	v_pk_mul_f32 v[0:1], v[0:1], v[182:183] op_sel_hi:[1,0]
	v_pk_mul_f32 v[2:3], v[2:3], v[182:183] op_sel_hi:[1,0]
	v_pk_mul_f32 v[8:9], v[8:9], v[182:183] op_sel_hi:[1,0]
	v_pk_mul_f32 v[10:11], v[10:11], v[182:183] op_sel_hi:[1,0]
	v_pk_mul_f32 v[16:17], v[16:17], v[182:183] op_sel_hi:[1,0]
	v_pk_mul_f32 v[18:19], v[18:19], v[182:183] op_sel_hi:[1,0]
	v_pk_mul_f32 v[24:25], v[24:25], v[182:183] op_sel_hi:[1,0]
	v_pk_mul_f32 v[26:27], v[26:27], v[182:183] op_sel_hi:[1,0]
	v_pk_mul_f32 v[32:33], v[32:33], v[182:183] op_sel_hi:[1,0]
	v_pk_mul_f32 v[34:35], v[34:35], v[182:183] op_sel_hi:[1,0]
	v_pk_mul_f32 v[40:41], v[40:41], v[182:183] op_sel_hi:[1,0]
	v_pk_mul_f32 v[42:43], v[42:43], v[182:183] op_sel_hi:[1,0]
	v_pk_mul_f32 v[48:49], v[48:49], v[182:183] op_sel_hi:[1,0]
	v_pk_mul_f32 v[50:51], v[50:51], v[182:183] op_sel_hi:[1,0]
	v_pk_mul_f32 v[56:57], v[56:57], v[182:183] op_sel_hi:[1,0]
	v_pk_mul_f32 v[58:59], v[58:59], v[182:183] op_sel_hi:[1,0]

.Lat_noload_B:
	v_add_u32_e32 v193, s44, v164
	v_add_u32_e32 v194, s0, v168
	v_add_u32_e32 v252, s1, v168
	s_setprio 0
	s_nop 0
	v_mfma_f32_16x16x32_bf16 v[0:3], v[204:207], v[236:239], v[0:3]
	v_mfma_f32_16x16x32_bf16 v[4:7], v[204:207], v[244:247], v[4:7]
	ds_read_b128 v[204:207], v194 offset:10240
	v_mfma_f32_16x16x32_bf16 v[0:3], v[208:211], v[240:243], v[0:3]
	v_mfma_f32_16x16x32_bf16 v[4:7], v[208:211], v[248:251], v[4:7]
	ds_read_b128 v[208:211], v194 offset:10304
	v_mfma_f32_16x16x32_bf16 v[8:11], v[212:215], v[236:239], v[8:11]
	v_mfma_f32_16x16x32_bf16 v[12:15], v[212:215], v[244:247], v[12:15]
	ds_read_b128 v[212:215], v194 offset:12800
	v_mfma_f32_16x16x32_bf16 v[8:11], v[216:219], v[240:243], v[8:11]
	v_mfma_f32_16x16x32_bf16 v[12:15], v[216:219], v[248:251], v[12:15]
	ds_read_b128 v[216:219], v194 offset:12864
	v_mfma_f32_16x16x32_bf16 v[16:19], v[220:223], v[236:239], v[16:19]
	v_mfma_f32_16x16x32_bf16 v[20:23], v[220:223], v[244:247], v[20:23]
	ds_read_b128 v[220:223], v194 offset:15360
	v_mfma_f32_16x16x32_bf16 v[16:19], v[224:227], v[240:243], v[16:19]
	v_mfma_f32_16x16x32_bf16 v[20:23], v[224:227], v[248:251], v[20:23]
	ds_read_b128 v[224:227], v194 offset:15424
	v_mfma_f32_16x16x32_bf16 v[24:27], v[228:231], v[236:239], v[24:27]
	v_mfma_f32_16x16x32_bf16 v[28:31], v[228:231], v[244:247], v[28:31]
	ds_read_b128 v[228:231], v194 offset:17920
	v_mfma_f32_16x16x32_bf16 v[24:27], v[232:235], v[240:243], v[24:27]
	v_mfma_f32_16x16x32_bf16 v[28:31], v[232:235], v[248:251], v[28:31]
	ds_read_b128 v[232:235], v194 offset:17984
	s_waitcnt lgkmcnt(7)
	v_mfma_f32_16x16x32_bf16 v[32:35], v[204:207], v[236:239], v[32:35]
	v_mfma_f32_16x16x32_bf16 v[36:39], v[204:207], v[244:247], v[36:39]
	ds_read_b128 v[204:207], v193
	s_waitcnt lgkmcnt(7)
	v_mfma_f32_16x16x32_bf16 v[32:35], v[208:211], v[240:243], v[32:35]
	v_mfma_f32_16x16x32_bf16 v[36:39], v[208:211], v[248:251], v[36:39]
	ds_read_b128 v[208:211], v193 offset:6656
	s_waitcnt lgkmcnt(7)
	v_mfma_f32_16x16x32_bf16 v[40:43], v[212:215], v[236:239], v[40:43]
	v_mfma_f32_16x16x32_bf16 v[44:47], v[212:215], v[244:247], v[44:47]
	ds_read_b128 v[212:215], v193 offset:13312
	s_waitcnt lgkmcnt(7)
	v_mfma_f32_16x16x32_bf16 v[40:43], v[216:219], v[240:243], v[40:43]
	v_mfma_f32_16x16x32_bf16 v[44:47], v[216:219], v[248:251], v[44:47]
	ds_read_b128 v[216:219], v193 offset:19968
	s_waitcnt lgkmcnt(7)
	v_mfma_f32_16x16x32_bf16 v[48:51], v[220:223], v[236:239], v[48:51]
	v_mfma_f32_16x16x32_bf16 v[52:55], v[220:223], v[244:247], v[52:55]
	ds_read_b128 v[220:223], v193 offset:64
	s_waitcnt lgkmcnt(7)
	v_mfma_f32_16x16x32_bf16 v[48:51], v[224:227], v[240:243], v[48:51]
	v_mfma_f32_16x16x32_bf16 v[52:55], v[224:227], v[248:251], v[52:55]
	ds_read_b128 v[224:227], v193 offset:6720
	s_waitcnt lgkmcnt(7)
	v_mfma_f32_16x16x32_bf16 v[56:59], v[228:231], v[236:239], v[56:59]
	v_mfma_f32_16x16x32_bf16 v[60:63], v[228:231], v[244:247], v[60:63]
	ds_read_b128 v[228:231], v193 offset:13376
	s_waitcnt lgkmcnt(7)
	v_mfma_f32_16x16x32_bf16 v[56:59], v[232:235], v[240:243], v[56:59]
	v_mfma_f32_16x16x32_bf16 v[60:63], v[232:235], v[248:251], v[60:63]
	ds_read_b128 v[232:235], v193 offset:20032
	s_setprio 1
	s_setprio 0
	s_waitcnt lgkmcnt(7)
	v_mfma_f32_16x16x32_bf16 v[132:135], v[204:207], v[64:67], 0
	v_mfma_f32_16x16x32_bf16 v[136:139], v[204:207], v[88:91], 0
	ds_read_b128 v[204:207], v193 offset:128
	s_waitcnt lgkmcnt(7)
	v_mfma_f32_16x16x32_bf16 v[140:143], v[208:211], v[64:67], 0
	v_mfma_f32_16x16x32_bf16 v[144:147], v[208:211], v[88:91], 0
	ds_read_b128 v[208:211], v193 offset:6784
	s_waitcnt lgkmcnt(7)
	v_mfma_f32_16x16x32_bf16 v[148:151], v[212:215], v[64:67], 0
	v_mfma_f32_16x16x32_bf16 v[152:155], v[212:215], v[88:91], 0
	ds_read_b128 v[212:215], v193 offset:13440
	s_waitcnt lgkmcnt(7)
	v_mfma_f32_16x16x32_bf16 v[156:159], v[216:219], v[64:67], 0
	v_mfma_f32_16x16x32_bf16 v[160:163], v[216:219], v[88:91], 0
	ds_read_b128 v[216:219], v193 offset:20096
	s_waitcnt lgkmcnt(7)
	v_mfma_f32_16x16x32_bf16 v[132:135], v[220:223], v[68:71], v[132:135]
	v_mfma_f32_16x16x32_bf16 v[136:139], v[220:223], v[92:95], v[136:139]
	ds_read_b128 v[220:223], v193 offset:192
	s_waitcnt lgkmcnt(7)
	v_mfma_f32_16x16x32_bf16 v[140:143], v[224:227], v[68:71], v[140:143]
	v_mfma_f32_16x16x32_bf16 v[144:147], v[224:227], v[92:95], v[144:147]
	ds_read_b128 v[224:227], v193 offset:6848
	s_waitcnt lgkmcnt(7)
	v_mfma_f32_16x16x32_bf16 v[148:151], v[228:231], v[68:71], v[148:151]
	v_mfma_f32_16x16x32_bf16 v[152:155], v[228:231], v[92:95], v[152:155]
	ds_read_b128 v[228:231], v193 offset:13504
	s_waitcnt lgkmcnt(7)
	v_mfma_f32_16x16x32_bf16 v[156:159], v[232:235], v[68:71], v[156:159]
	v_mfma_f32_16x16x32_bf16 v[160:163], v[232:235], v[92:95], v[160:163]
	ds_read_b128 v[232:235], v193 offset:20160
	s_waitcnt lgkmcnt(7)
	v_mfma_f32_16x16x32_bf16 v[132:135], v[204:207], v[72:75], v[132:135]
	v_mfma_f32_16x16x32_bf16 v[136:139], v[204:207], v[96:99], v[136:139]
	ds_read_b128 v[204:207], v193 offset:256
	s_waitcnt lgkmcnt(7)
	v_mfma_f32_16x16x32_bf16 v[140:143], v[208:211], v[72:75], v[140:143]
	v_mfma_f32_16x16x32_bf16 v[144:147], v[208:211], v[96:99], v[144:147]
	ds_read_b128 v[208:211], v193 offset:6912
	s_waitcnt lgkmcnt(7)
	v_mfma_f32_16x16x32_bf16 v[148:151], v[212:215], v[72:75], v[148:151]
	v_mfma_f32_16x16x32_bf16 v[152:155], v[212:215], v[96:99], v[152:155]
	ds_read_b128 v[212:215], v193 offset:13568
	s_waitcnt lgkmcnt(7)
	v_mfma_f32_16x16x32_bf16 v[156:159], v[216:219], v[72:75], v[156:159]
	v_mfma_f32_16x16x32_bf16 v[160:163], v[216:219], v[96:99], v[160:163]
	ds_read_b128 v[216:219], v193 offset:20224
	s_waitcnt lgkmcnt(7)
	v_mfma_f32_16x16x32_bf16 v[132:135], v[220:223], v[76:79], v[132:135]
	v_mfma_f32_16x16x32_bf16 v[136:139], v[220:223], v[100:103], v[136:139]
	ds_read_b128 v[220:223], v193 offset:320
	s_waitcnt lgkmcnt(7)
	v_mfma_f32_16x16x32_bf16 v[140:143], v[224:227], v[76:79], v[140:143]
	v_mfma_f32_16x16x32_bf16 v[144:147], v[224:227], v[100:103], v[144:147]
	ds_read_b128 v[224:227], v193 offset:6976
	s_waitcnt lgkmcnt(7)
	v_mfma_f32_16x16x32_bf16 v[148:151], v[228:231], v[76:79], v[148:151]
	v_mfma_f32_16x16x32_bf16 v[152:155], v[228:231], v[100:103], v[152:155]
	ds_read_b128 v[228:231], v193 offset:13632
	s_waitcnt lgkmcnt(7)
	v_mfma_f32_16x16x32_bf16 v[156:159], v[232:235], v[76:79], v[156:159]
	v_mfma_f32_16x16x32_bf16 v[160:163], v[232:235], v[100:103], v[160:163]
	ds_read_b128 v[232:235], v193 offset:20288
	s_waitcnt lgkmcnt(7)
	v_mfma_f32_16x16x32_bf16 v[132:135], v[204:207], v[80:83], v[132:135]
	v_mfma_f32_16x16x32_bf16 v[136:139], v[204:207], v[104:107], v[136:139]
	ds_read_b128 v[204:207], v252
	s_waitcnt lgkmcnt(7)
	v_mfma_f32_16x16x32_bf16 v[140:143], v[208:211], v[80:83], v[140:143]
	v_mfma_f32_16x16x32_bf16 v[144:147], v[208:211], v[104:107], v[144:147]
	ds_read_b128 v[208:211], v252 offset:64
	s_waitcnt lgkmcnt(7)
	v_mfma_f32_16x16x32_bf16 v[148:151], v[212:215], v[80:83], v[148:151]
	v_mfma_f32_16x16x32_bf16 v[152:155], v[212:215], v[104:107], v[152:155]
	ds_read_b128 v[212:215], v252 offset:2560
	s_waitcnt lgkmcnt(7)
	v_mfma_f32_16x16x32_bf16 v[156:159], v[216:219], v[80:83], v[156:159]
	v_mfma_f32_16x16x32_bf16 v[160:163], v[216:219], v[104:107], v[160:163]
	ds_read_b128 v[216:219], v252 offset:2624
	s_waitcnt lgkmcnt(7)
	v_mfma_f32_16x16x32_bf16 v[132:135], v[220:223], v[84:87], v[132:135]
	v_mfma_f32_16x16x32_bf16 v[136:139], v[220:223], v[108:111], v[136:139]
	ds_read_b128 v[220:223], v252 offset:5120
	s_waitcnt lgkmcnt(7)
	v_mfma_f32_16x16x32_bf16 v[140:143], v[224:227], v[84:87], v[140:143]
	v_mfma_f32_16x16x32_bf16 v[144:147], v[224:227], v[108:111], v[144:147]
	ds_read_b128 v[224:227], v252 offset:5184
	s_waitcnt lgkmcnt(7)
	v_mfma_f32_16x16x32_bf16 v[148:151], v[228:231], v[84:87], v[148:151]
	v_mfma_f32_16x16x32_bf16 v[152:155], v[228:231], v[108:111], v[152:155]
	ds_read_b128 v[228:231], v252 offset:7680
	s_waitcnt lgkmcnt(7)
	v_mfma_f32_16x16x32_bf16 v[156:159], v[232:235], v[84:87], v[156:159]
	v_mfma_f32_16x16x32_bf16 v[160:163], v[232:235], v[108:111], v[160:163]
	ds_read_b128 v[232:235], v252 offset:7744
	s_setprio 1
	s_nop 6
	v_max3_f32 v199, v132, v133, v134
	v_max3_f32 v200, v136, v137, v138
	v_max3_f32 v199, v199, v135, v140
	v_max3_f32 v200, v200, v139, v144
	v_max3_f32 v199, v199, v141, v142
	v_max3_f32 v200, v200, v145, v146
	v_max3_f32 v199, v199, v143, v148
	v_max3_f32 v200, v200, v147, v152
	v_max3_f32 v199, v199, v149, v150
	v_max3_f32 v200, v200, v153, v154
	v_max3_f32 v199, v199, v151, v156
	v_max3_f32 v200, v200, v155, v160
	v_max3_f32 v199, v199, v157, v158
	v_max3_f32 v200, v200, v161, v162
	v_max_f32_e32 v199, v199, v159
	v_max_f32_e32 v200, v200, v163
	v_mov_b32_e32 v253, v199
	v_mov_b32_e32 v201, v200
	s_nop 1
	v_permlane16_swap_b32_e32 v199, v253
	v_permlane16_swap_b32_e32 v200, v201
	s_nop 0
	v_max_f32_e32 v199, v199, v253
	v_max_f32_e32 v200, v200, v201
	v_mov_b32_e32 v253, v199
	v_mov_b32_e32 v201, v200
	s_nop 1
	v_permlane32_swap_b32_e32 v199, v253
	v_permlane32_swap_b32_e32 v200, v201
	s_nop 0
	v_max_f32_e32 v199, v199, v253
	v_max_f32_e32 v200, v200, v201
	v_max_f32_e32 v199, v177, v199
	v_max_f32_e32 v200, v178, v200
	v_sub_f32_e32 v182, v177, v199
	v_sub_f32_e32 v202, v178, v200
	v_exp_f32_e32 v182, v182
	v_exp_f32_e32 v202, v202
	v_mov_b32_e32 v177, v199
	v_mov_b32_e32 v178, v200
	v_sub_f32_e32 v132, v132, v177
	v_sub_f32_e32 v136, v136, v178
	v_sub_f32_e32 v133, v133, v177
	v_sub_f32_e32 v137, v137, v178
	v_sub_f32_e32 v134, v134, v177
	v_sub_f32_e32 v138, v138, v178
	v_sub_f32_e32 v135, v135, v177
	v_sub_f32_e32 v139, v139, v178
	v_sub_f32_e32 v140, v140, v177
	v_sub_f32_e32 v144, v144, v178
	v_sub_f32_e32 v141, v141, v177
	v_sub_f32_e32 v145, v145, v178
	v_sub_f32_e32 v142, v142, v177
	v_sub_f32_e32 v146, v146, v178
	v_sub_f32_e32 v143, v143, v177
	v_sub_f32_e32 v147, v147, v178
	v_sub_f32_e32 v148, v148, v177
	v_sub_f32_e32 v152, v152, v178
	v_sub_f32_e32 v149, v149, v177
	v_sub_f32_e32 v153, v153, v178
	v_sub_f32_e32 v150, v150, v177
	v_sub_f32_e32 v154, v154, v178
	v_sub_f32_e32 v151, v151, v177
	v_sub_f32_e32 v155, v155, v178
	v_sub_f32_e32 v156, v156, v177
	v_sub_f32_e32 v160, v160, v178
	v_sub_f32_e32 v157, v157, v177
	v_sub_f32_e32 v161, v161, v178
	v_sub_f32_e32 v158, v158, v177
	v_sub_f32_e32 v162, v162, v178
	v_sub_f32_e32 v159, v159, v177
	v_sub_f32_e32 v163, v163, v178
	v_exp_f32_e32 v132, v132
	v_exp_f32_e32 v136, v136
	v_exp_f32_e32 v133, v133
	v_exp_f32_e32 v137, v137
	v_exp_f32_e32 v134, v134
	v_exp_f32_e32 v138, v138
	v_exp_f32_e32 v135, v135
	v_exp_f32_e32 v139, v139
	v_exp_f32_e32 v140, v140
	v_exp_f32_e32 v144, v144
	v_exp_f32_e32 v141, v141
	v_exp_f32_e32 v145, v145
	v_exp_f32_e32 v142, v142
	v_exp_f32_e32 v146, v146
	v_exp_f32_e32 v143, v143
	v_exp_f32_e32 v147, v147
	v_exp_f32_e32 v148, v148
	v_exp_f32_e32 v152, v152
	v_exp_f32_e32 v149, v149
	v_exp_f32_e32 v153, v153
	v_exp_f32_e32 v150, v150
	v_exp_f32_e32 v154, v154
	v_exp_f32_e32 v151, v151
	v_exp_f32_e32 v155, v155
	v_exp_f32_e32 v156, v156
	v_exp_f32_e32 v160, v160
	v_exp_f32_e32 v157, v157
	v_exp_f32_e32 v161, v161
	v_exp_f32_e32 v158, v158
	v_exp_f32_e32 v162, v162
	v_exp_f32_e32 v159, v159
	v_exp_f32_e32 v163, v163
	v_cmp_eq_f32_e32 vcc, 1.0, v182
	s_cmp_eq_u64 vcc, exec
	s_cbranch_scc1 .Lat_noscale0_B
	v_pk_mul_f32 v[0:1], v[0:1], v[182:183] op_sel_hi:[1,0]
	v_pk_mul_f32 v[2:3], v[2:3], v[182:183] op_sel_hi:[1,0]
	v_pk_mul_f32 v[8:9], v[8:9], v[182:183] op_sel_hi:[1,0]
	v_pk_mul_f32 v[10:11], v[10:11], v[182:183] op_sel_hi:[1,0]
	v_pk_mul_f32 v[16:17], v[16:17], v[182:183] op_sel_hi:[1,0]
	v_pk_mul_f32 v[18:19], v[18:19], v[182:183] op_sel_hi:[1,0]
	v_pk_mul_f32 v[24:25], v[24:25], v[182:183] op_sel_hi:[1,0]
	v_pk_mul_f32 v[26:27], v[26:27], v[182:183] op_sel_hi:[1,0]
	v_pk_mul_f32 v[32:33], v[32:33], v[182:183] op_sel_hi:[1,0]
	v_pk_mul_f32 v[34:35], v[34:35], v[182:183] op_sel_hi:[1,0]
	v_pk_mul_f32 v[40:41], v[40:41], v[182:183] op_sel_hi:[1,0]
	v_pk_mul_f32 v[42:43], v[42:43], v[182:183] op_sel_hi:[1,0]
	v_pk_mul_f32 v[48:49], v[48:49], v[182:183] op_sel_hi:[1,0]
	v_pk_mul_f32 v[50:51], v[50:51], v[182:183] op_sel_hi:[1,0]
	v_pk_mul_f32 v[56:57], v[56:57], v[182:183] op_sel_hi:[1,0]
	v_pk_mul_f32 v[58:59], v[58:59], v[182:183] op_sel_hi:[1,0]

.Lat_nostage_B:
	s_xor_b32 s44, s44, 26624
	s_mov_b32 s12, s0
	s_mov_b32 s0, s1
	s_mov_b32 s1, s13
	s_mov_b32 s13, s12
	s_add_u32 s35, s35, 1
	s_waitcnt lgkmcnt(0)
	s_barrier
	s_cmpk_lt_u32 s35, 68
	s_cbranch_scc1 .Lat_B_loop
	v_add_u32_e32 v194, s0, v168
	s_setprio 0
	s_nop 0
	v_mfma_f32_16x16x32_bf16 v[0:3], v[204:207], v[236:239], v[0:3]
	v_mfma_f32_16x16x32_bf16 v[4:7], v[204:207], v[244:247], v[4:7]
	ds_read_b128 v[204:207], v194 offset:10240
	v_mfma_f32_16x16x32_bf16 v[0:3], v[208:211], v[240:243], v[0:3]
	v_mfma_f32_16x16x32_bf16 v[4:7], v[208:211], v[248:251], v[4:7]
	ds_read_b128 v[208:211], v194 offset:10304
	v_mfma_f32_16x16x32_bf16 v[8:11], v[212:215], v[236:239], v[8:11]
	v_mfma_f32_16x16x32_bf16 v[12:15], v[212:215], v[244:247], v[12:15]
	ds_read_b128 v[212:215], v194 offset:12800
	v_mfma_f32_16x16x32_bf16 v[8:11], v[216:219], v[240:243], v[8:11]
	v_mfma_f32_16x16x32_bf16 v[12:15], v[216:219], v[248:251], v[12:15]
	ds_read_b128 v[216:219], v194 offset:12864
	v_mfma_f32_16x16x32_bf16 v[16:19], v[220:223], v[236:239], v[16:19]
	v_mfma_f32_16x16x32_bf16 v[20:23], v[220:223], v[244:247], v[20:23]
	ds_read_b128 v[220:223], v194 offset:15360
	v_mfma_f32_16x16x32_bf16 v[16:19], v[224:227], v[240:243], v[16:19]
	v_mfma_f32_16x16x32_bf16 v[20:23], v[224:227], v[248:251], v[20:23]
	ds_read_b128 v[224:227], v194 offset:15424
	v_mfma_f32_16x16x32_bf16 v[24:27], v[228:231], v[236:239], v[24:27]
	v_mfma_f32_16x16x32_bf16 v[28:31], v[228:231], v[244:247], v[28:31]
	ds_read_b128 v[228:231], v194 offset:17920
	v_mfma_f32_16x16x32_bf16 v[24:27], v[232:235], v[240:243], v[24:27]
	v_mfma_f32_16x16x32_bf16 v[28:31], v[232:235], v[248:251], v[28:31]
	ds_read_b128 v[232:235], v194 offset:17984
	s_waitcnt lgkmcnt(7)
	v_mfma_f32_16x16x32_bf16 v[32:35], v[204:207], v[236:239], v[32:35]
	v_mfma_f32_16x16x32_bf16 v[36:39], v[204:207], v[244:247], v[36:39]
	s_waitcnt lgkmcnt(6)
	v_mfma_f32_16x16x32_bf16 v[32:35], v[208:211], v[240:243], v[32:35]
	v_mfma_f32_16x16x32_bf16 v[36:39], v[208:211], v[248:251], v[36:39]
	s_waitcnt lgkmcnt(5)
	v_mfma_f32_16x16x32_bf16 v[40:43], v[212:215], v[236:239], v[40:43]
	v_mfma_f32_16x16x32_bf16 v[44:47], v[212:215], v[244:247], v[44:47]
	s_waitcnt lgkmcnt(4)
	v_mfma_f32_16x16x32_bf16 v[40:43], v[216:219], v[240:243], v[40:43]
	v_mfma_f32_16x16x32_bf16 v[44:47], v[216:219], v[248:251], v[44:47]
	s_waitcnt lgkmcnt(3)
	v_mfma_f32_16x16x32_bf16 v[48:51], v[220:223], v[236:239], v[48:51]
	v_mfma_f32_16x16x32_bf16 v[52:55], v[220:223], v[244:247], v[52:55]
	s_waitcnt lgkmcnt(2)
	v_mfma_f32_16x16x32_bf16 v[48:51], v[224:227], v[240:243], v[48:51]
	v_mfma_f32_16x16x32_bf16 v[52:55], v[224:227], v[248:251], v[52:55]
	s_waitcnt lgkmcnt(1)
	v_mfma_f32_16x16x32_bf16 v[56:59], v[228:231], v[236:239], v[56:59]
	v_mfma_f32_16x16x32_bf16 v[60:63], v[228:231], v[244:247], v[60:63]
	s_waitcnt lgkmcnt(0)
	v_mfma_f32_16x16x32_bf16 v[56:59], v[232:235], v[240:243], v[56:59]
	v_mfma_f32_16x16x32_bf16 v[60:63], v[232:235], v[248:251], v[60:63]
	s_setprio 1
	s_waitcnt lgkmcnt(0)
.Lat_join:
	s_setprio 0
	s_barrier
	v_mov_b32_e32 v253, v179
	v_mov_b32_e32 v201, v180
	s_nop 1
	v_permlane16_swap_b32_e32 v179, v253
	v_permlane16_swap_b32_e32 v180, v201
	s_nop 0
	v_add_f32_e32 v179, v179, v253
	v_add_f32_e32 v180, v180, v201
	v_mov_b32_e32 v253, v179
	v_mov_b32_e32 v201, v180
	s_nop 1
	v_permlane32_swap_b32_e32 v179, v253
	v_permlane32_swap_b32_e32 v180, v201
	s_nop 0
	v_add_f32_e32 v179, v179, v253
	v_add_f32_e32 v180, v180, v201
	v_div_scale_f32 v64, s[0:1], v179, v179, 1.0
	v_rcp_f32_e32 v65, v64
	s_nop 0
	v_fma_f32 v66, -v64, v65, 1.0
	v_fmac_f32_e32 v65, v66, v65
	v_div_scale_f32 v66, vcc, 1.0, v179, 1.0
	v_mul_f32_e32 v67, v66, v65
	v_fma_f32 v68, -v64, v67, v66
	v_fmac_f32_e32 v67, v68, v65
	v_fma_f32 v64, -v64, v67, v66
	s_nop 0
	v_div_fmas_f32 v64, v64, v65, v67
	v_div_fixup_f32 v199, v64, v179, 1.0
	v_div_scale_f32 v64, s[0:1], v180, v180, 1.0
	v_rcp_f32_e32 v65, v64
	s_nop 0
	v_fma_f32 v66, -v64, v65, 1.0
	v_fmac_f32_e32 v65, v66, v65
	v_div_scale_f32 v66, vcc, 1.0, v180, 1.0
	v_mul_f32_e32 v67, v66, v65
	v_fma_f32 v68, -v64, v67, v66
	v_fmac_f32_e32 v67, v68, v65
	v_fma_f32 v64, -v64, v67, v66
	s_nop 0
	v_div_fmas_f32 v64, v64, v65, v67
	v_div_fixup_f32 v200, v64, v180, 1.0
	s_and_b32 s0, s34, 7
	s_ashr_i32 s12, s34, 7
	s_lshl_b32 s13, s34, 5
	s_and_b32 s13, s13, 0xf00
	s_lshl_b32 s1, s12, 12
	s_or_b32 s13, s13, s1
	s_lshl_b32 s13, s13, 12
	s_lshl_b32 s0, s0, 8
	s_add_u32 s13, s13, s0
	s_add_u32 s0, s10, s13
	s_addc_u32 s1, s11, 0
	v_and_b32_e32 v73, 15, v167
	v_lshrrev_b32_e32 v72, 6, v167
	v_lshl_add_u32 v72, v72, 5, v73
	v_lshlrev_b32_e32 v72, 12, v72
	v_bfe_u32 v73, v167, 4, 2
	v_lshl_add_u32 v72, v73, 3, v72
	v_add_u32_e32 v73, 0x10000, v72
	v_mul_f32_e32 v0, v0, v199
	v_mul_f32_e32 v1, v1, v199
	v_mul_f32_e32 v2, v2, v199
	v_mul_f32_e32 v3, v3, v199
	v_cvt_pk_bf16_f32 v0, v0, v1
	v_cvt_pk_bf16_f32 v1, v2, v3
	global_store_dwordx2 v72, v[0:1], s[0:1]
	v_mul_f32_e32 v8, v8, v199
	v_mul_f32_e32 v9, v9, v199
	v_mul_f32_e32 v10, v10, v199
	v_mul_f32_e32 v11, v11, v199
	v_cvt_pk_bf16_f32 v8, v8, v9
	v_cvt_pk_bf16_f32 v9, v10, v11
	global_store_dwordx2 v72, v[8:9], s[0:1] offset:32
	v_mul_f32_e32 v16, v16, v199
	v_mul_f32_e32 v17, v17, v199
	v_mul_f32_e32 v18, v18, v199
	v_mul_f32_e32 v19, v19, v199
	v_cvt_pk_bf16_f32 v16, v16, v17
	v_cvt_pk_bf16_f32 v17, v18, v19
	global_store_dwordx2 v72, v[16:17], s[0:1] offset:64
	v_mul_f32_e32 v24, v24, v199
	v_mul_f32_e32 v25, v25, v199
	v_mul_f32_e32 v26, v26, v199
	v_mul_f32_e32 v27, v27, v199
	v_cvt_pk_bf16_f32 v24, v24, v25
	v_cvt_pk_bf16_f32 v25, v26, v27
	global_store_dwordx2 v72, v[24:25], s[0:1] offset:96
	v_mul_f32_e32 v32, v32, v199
	v_mul_f32_e32 v33, v33, v199
	v_mul_f32_e32 v34, v34, v199
	v_mul_f32_e32 v35, v35, v199
	v_cvt_pk_bf16_f32 v32, v32, v33
	v_cvt_pk_bf16_f32 v33, v34, v35
	global_store_dwordx2 v72, v[32:33], s[0:1] offset:128
	v_mul_f32_e32 v40, v40, v199
	v_mul_f32_e32 v41, v41, v199
	v_mul_f32_e32 v42, v42, v199
	v_mul_f32_e32 v43, v43, v199
	v_cvt_pk_bf16_f32 v40, v40, v41
	v_cvt_pk_bf16_f32 v41, v42, v43
	global_store_dwordx2 v72, v[40:41], s[0:1] offset:160
	v_mul_f32_e32 v48, v48, v199
	v_mul_f32_e32 v49, v49, v199
	v_mul_f32_e32 v50, v50, v199
	v_mul_f32_e32 v51, v51, v199
	v_cvt_pk_bf16_f32 v48, v48, v49
	v_cvt_pk_bf16_f32 v49, v50, v51
	global_store_dwordx2 v72, v[48:49], s[0:1] offset:192
	v_mul_f32_e32 v56, v56, v199
	v_mul_f32_e32 v57, v57, v199
	v_mul_f32_e32 v58, v58, v199
	v_mul_f32_e32 v59, v59, v199
	v_cvt_pk_bf16_f32 v56, v56, v57
	v_cvt_pk_bf16_f32 v57, v58, v59
	global_store_dwordx2 v72, v[56:57], s[0:1] offset:224
	v_mul_f32_e32 v4, v4, v200
	v_mul_f32_e32 v5, v5, v200
	v_mul_f32_e32 v6, v6, v200
	v_mul_f32_e32 v7, v7, v200
	v_cvt_pk_bf16_f32 v4, v4, v5
	v_cvt_pk_bf16_f32 v5, v6, v7
	global_store_dwordx2 v73, v[4:5], s[0:1]
	v_mul_f32_e32 v12, v12, v200
	v_mul_f32_e32 v13, v13, v200
	v_mul_f32_e32 v14, v14, v200
	v_mul_f32_e32 v15, v15, v200
	v_cvt_pk_bf16_f32 v12, v12, v13
	v_cvt_pk_bf16_f32 v13, v14, v15
	global_store_dwordx2 v73, v[12:13], s[0:1] offset:32
	v_mul_f32_e32 v20, v20, v200
	v_mul_f32_e32 v21, v21, v200
	v_mul_f32_e32 v22, v22, v200
	v_mul_f32_e32 v23, v23, v200
	v_cvt_pk_bf16_f32 v20, v20, v21
	v_cvt_pk_bf16_f32 v21, v22, v23
	global_store_dwordx2 v73, v[20:21], s[0:1] offset:64
	v_mul_f32_e32 v28, v28, v200
	v_mul_f32_e32 v29, v29, v200
	v_mul_f32_e32 v30, v30, v200
	v_mul_f32_e32 v31, v31, v200
	v_cvt_pk_bf16_f32 v28, v28, v29
	v_cvt_pk_bf16_f32 v29, v30, v31
	global_store_dwordx2 v73, v[28:29], s[0:1] offset:96
	v_mul_f32_e32 v36, v36, v200
	v_mul_f32_e32 v37, v37, v200
	v_mul_f32_e32 v38, v38, v200
	v_mul_f32_e32 v39, v39, v200
	v_cvt_pk_bf16_f32 v36, v36, v37
	v_cvt_pk_bf16_f32 v37, v38, v39
	global_store_dwordx2 v73, v[36:37], s[0:1] offset:128
	v_mul_f32_e32 v44, v44, v200
	v_mul_f32_e32 v45, v45, v200
	v_mul_f32_e32 v46, v46, v200
	v_mul_f32_e32 v47, v47, v200
	v_cvt_pk_bf16_f32 v44, v44, v45
	v_cvt_pk_bf16_f32 v45, v46, v47
	global_store_dwordx2 v73, v[44:45], s[0:1] offset:160
	v_mul_f32_e32 v52, v52, v200
	v_mul_f32_e32 v53, v53, v200
	v_mul_f32_e32 v54, v54, v200
	v_mul_f32_e32 v55, v55, v200
	v_cvt_pk_bf16_f32 v52, v52, v53
	v_cvt_pk_bf16_f32 v53, v54, v55
	global_store_dwordx2 v73, v[52:53], s[0:1] offset:192
	v_mul_f32_e32 v60, v60, v200
	v_mul_f32_e32 v61, v61, v200
	v_mul_f32_e32 v62, v62, v200
	v_mul_f32_e32 v63, v63, v200
	v_cvt_pk_bf16_f32 v60, v60, v61
	v_cvt_pk_bf16_f32 v61, v62, v63
	global_store_dwordx2 v73, v[60:61], s[0:1] offset:224
	v_readlane_b32 s0, v254, 1
	s_add_i32 s34, s34, s0
	s_add_i32 s9, s9, s0
	s_add_i32 s8, s8, s0
	s_cmp_lt_i32 s34, s40
	v_readlane_b32 s1, v254, 2
	s_cbranch_scc0 .LBB0_1033
	s_branch .LBB0_1008
